# baseline (speedup 1.0000x reference)
; __device__ __forceinline__ float bfs(short h) { return __uint_as_float(((unsigned)(u16)h) << 16); }
; template <int lda, int K>
; __device__ __forceinline__ void phase_resid(PP p, const int g_wid, const u16* Abase, const u16* Btbase, const float alpha_in) {
;     ...
;     const unsigned tok0 = wc * 32 + fr;
; #pragma unroll
;     for (int bj = 0; bj < 2; ++bj)
; #pragma unroll
;       for (int n = 0; n < 2; ++n) {
;         const int row = pm * 256 + tok0 + bj * 128 + n * 16;
;         const bool ok = row < NTOK;
;         float sq = 0.f;
;         u16* hbr = p->hb + (long)row * 1024 + pn * 256 + wr * 64 + SWAP_FOFF(fq);
; #pragma unroll
;         for (int ai = 0; ai < 2; ++ai)
; #pragma unroll
;           for (int mp = 0; mp < 4; mp += 2) {
;             float v[8];
; #pragma unroll
;             for (int j = 0; j < 4; ++j) {
;               auto r = __builtin_amdgcn_permlane16_swap(__float_as_uint(acc[ai][bj][mp][n][j]), __float_as_uint(acc[ai][bj][mp + 1][n][j]), false, false);
;               v[j] = __uint_as_float(r[0]); v[4 + j] = __uint_as_float(r[1]);
;             }
;             if (ok) {
;               const bf16x8 ho = *reinterpret_cast<const bf16x8*>(hbr + ai * 128 + mp * 16);
; #pragma unroll
;               for (int j = 0; j < 8; ++j) { v[j] = bfs(ho[j]) + alpha * v[j]; sq += v[j] * v[j]; }
;               *reinterpret_cast<uint4*>(hbr + ai * 128 + mp * 16) = make_uint4(pack2(v[0], v[1]), pack2(v[2], v[3]), pack2(v[4], v[5]), pack2(v[6], v[7]));
.LBB0_344:
	s_or_b64 exec, exec, s[2:3]
	s_mov_b32 s2, -1
	v_readlane_b32 s10, v254, 0
	v_mbcnt_lo_u32_b32 v0, s2, 0
	v_mbcnt_hi_u32_b32 v0, s2, v0
	v_readlane_b32 s2, v254, 63
	v_readlane_b32 s11, v254, 1
	s_lshl_b32 s14, s16, 8
	v_or_b32_e32 v0, s2, v0
	s_load_dwordx2 s[2:3], s[10:11], 0xc8
	s_load_dwordx2 s[12:13], s[10:11], 0xe0
	v_lshrrev_b32_e32 v133, 1, v0
	v_and_b32_e32 v132, 15, v0
	v_and_b32_e32 v133, 0x60, v133
	v_or3_b32 v132, v132, v133, s14
	s_lshl_b32 s14, s20, 8
	v_bfe_u32 v131, v0, 4, 2
	s_ashr_i32 s15, s14, 31
	v_ashrrev_i32_e32 v136, 8, v0
	s_lshl_b64 s[14:15], s[14:15], 1
	v_and_b32_e32 v0, 16, v0
	v_lshlrev_b32_e32 v133, 2, v131
	s_waitcnt lgkmcnt(0)
	s_add_u32 s2, s2, s14
	v_lshlrev_b32_e32 v134, 6, v136
	v_add_u32_e32 v137, 12, v133
	v_cmp_eq_u32_e32 vcc, 0, v0
	s_addc_u32 s3, s3, s15
	v_ashrrev_i32_e32 v135, 31, v134
	v_cndmask_b32_e32 v0, v137, v133, vcc
	v_lshl_add_u64 v[134:135], v[134:135], 1, s[2:3]
	v_lshlrev_b32_e32 v0, 1, v0
	v_ashrrev_i32_e32 v133, 31, v132
	v_lshl_add_u64 v[134:135], v[134:135], 0, v[0:1]
	v_lshlrev_b64 v[138:139], 11, v[132:133]
	v_mov_b32_e32 v130, 0.5
	v_cmp_gt_i32_e64 s[2:3], s47, v132
	v_lshl_add_u64 v[138:139], v[134:135], 0, v[138:139]
	v_and_b32_e32 v248, 15, v132
	v_lshl_or_b32 v245, v131, 4, v248
	v_lshrrev_b32_e32 v249, 5, v132
	v_and_b32_e32 v249, 3, v249
	v_lshl_or_b32 v249, v136, 2, v249
	v_lshlrev_b32_e32 v249, 14, v249
	v_and_b32_e32 v242, 1, v131
	v_lshrrev_b32_e32 v243, 1, v131
	v_lshl_or_b32 v243, v242, 1, v243
	v_and_b32_e32 v242, 7, v248
	v_xor_b32_e32 v242, v243, v242
	v_lshlrev_b32_e32 v242, 4, v242
	v_lshl_add_u32 v244, v248, 7, v249
	v_add_u32_e32 v242, v244, v242
	v_lshlrev_b32_e32 v243, 4, v243
	v_lshl_add_u32 v248, v248, 11, v243
	v_xor_b32_e32 v243, 64, v242
	v_lshrrev_b32_e32 v244, 3, v245
	v_and_b32_e32 v245, 7, v245
	v_lshlrev_b32_e32 v246, 4, v245
	v_lshl_add_u32 v246, v244, 11, v246
	v_sub_u32_e32 v246, v246, v248
	v_ashrrev_i32_e32 v247, 31, v246
	v_lshl_add_u64 v[246:247], v[138:139], 0, v[246:247]
	v_xor_b32_e32 v245, v245, v244
	v_lshlrev_b32_e32 v245, 4, v245
	v_lshl_add_u32 v244, v244, 7, v249
	v_add_u32_e32 v244, v244, v245
	global_load_dwordx4 v[178:181], v[246:247], off
	global_load_dwordx4 v[186:189], v[246:247], off offset:256
	v_add_co_u32_e32 v246, vcc, 0x4000, v246
	s_nop 1
	v_addc_co_u32_e32 v247, vcc, 0, v247, vcc
	global_load_dwordx4 v[182:185], v[246:247], off
	global_load_dwordx4 v[190:193], v[246:247], off offset:256
	v_add_co_u32_e32 v246, vcc, 0x4000, v246
	s_nop 1
	v_addc_co_u32_e32 v247, vcc, 0, v247, vcc
	global_load_dwordx4 v[194:197], v[246:247], off
	global_load_dwordx4 v[202:205], v[246:247], off offset:256
	v_add_co_u32_e32 v246, vcc, 0x4000, v246
	s_nop 1
	v_addc_co_u32_e32 v247, vcc, 0, v247, vcc
	global_load_dwordx4 v[198:201], v[246:247], off
	global_load_dwordx4 v[206:209], v[246:247], off offset:256
	v_add_co_u32_e32 v246, vcc, 0x34000, v246
	s_nop 1
	v_addc_co_u32_e32 v247, vcc, 0, v247, vcc
	global_load_dwordx4 v[210:213], v[246:247], off
	global_load_dwordx4 v[218:221], v[246:247], off offset:256
	v_add_co_u32_e32 v246, vcc, 0x4000, v246
	s_nop 1
	v_addc_co_u32_e32 v247, vcc, 0, v247, vcc
	global_load_dwordx4 v[214:217], v[246:247], off
	global_load_dwordx4 v[222:225], v[246:247], off offset:256
	v_add_co_u32_e32 v246, vcc, 0x4000, v246
	s_nop 1
	v_addc_co_u32_e32 v247, vcc, 0, v247, vcc
	global_load_dwordx4 v[226:229], v[246:247], off
	global_load_dwordx4 v[234:237], v[246:247], off offset:256
	v_add_co_u32_e32 v246, vcc, 0x4000, v246
	s_nop 1
	v_addc_co_u32_e32 v247, vcc, 0, v247, vcc
	global_load_dwordx4 v[230:233], v[246:247], off
	global_load_dwordx4 v[238:241], v[246:247], off offset:256
	s_waitcnt vmcnt(0)
	ds_write_b128 v244, v[178:181]
	ds_write_b128 v244, v[182:185] offset:1024
	ds_write_b128 v244, v[186:189] offset:2048
	ds_write_b128 v244, v[190:193] offset:3072
	ds_write_b128 v244, v[194:197] offset:4096
	ds_write_b128 v244, v[198:201] offset:5120
	ds_write_b128 v244, v[202:205] offset:6144
	ds_write_b128 v244, v[206:209] offset:7168
	ds_write_b128 v244, v[210:213] offset:8192
	ds_write_b128 v244, v[214:217] offset:9216
	ds_write_b128 v244, v[218:221] offset:10240
	ds_write_b128 v244, v[222:225] offset:11264
	ds_write_b128 v244, v[226:229] offset:12288
	ds_write_b128 v244, v[230:233] offset:13312
	ds_write_b128 v244, v[234:237] offset:14336
	ds_write_b128 v244, v[238:241] offset:15360
	ds_read_b128 v[178:181], v242
	ds_read_b128 v[182:185], v243
	ds_read_b128 v[186:189], v242 offset:2048
	ds_read_b128 v[190:193], v243 offset:2048
	ds_read_b128 v[194:197], v242 offset:4096
	ds_read_b128 v[198:201], v243 offset:4096
	ds_read_b128 v[202:205], v242 offset:6144
	ds_read_b128 v[206:209], v243 offset:6144
	ds_read_b128 v[210:213], v242 offset:8192
	ds_read_b128 v[214:217], v243 offset:8192
	ds_read_b128 v[218:221], v242 offset:10240
	ds_read_b128 v[222:225], v243 offset:10240
	ds_read_b128 v[226:229], v242 offset:12288
	ds_read_b128 v[230:233], v243 offset:12288
	ds_read_b128 v[234:237], v242 offset:14336
	ds_read_b128 v[238:241], v243 offset:14336
	s_waitcnt lgkmcnt(0)
	s_barrier
	v_permlane16_swap_b32_e32 v122, v126
	v_permlane16_swap_b32_e32 v123, v127
	v_permlane16_swap_b32_e32 v124, v128
	v_permlane16_swap_b32_e32 v125, v129
	v_mov_b32_e32 v140, 0
	s_and_saveexec_b64 s[14:15], s[2:3]
	s_cbranch_execz .LBB0_346
	s_waitcnt vmcnt(15)
	v_mov_b64_e32 v[140:141], v[178:179]
	v_mov_b64_e32 v[142:143], v[180:181]
	v_and_b32_e32 v145, 0xffff0000, v140
	v_lshlrev_b32_e32 v144, 16, v140
	v_and_b32_e32 v147, 0xffff0000, v141
	v_lshlrev_b32_e32 v146, 16, v141
	v_and_b32_e32 v141, 0xffff0000, v142
	v_lshlrev_b32_e32 v140, 16, v142
	v_pk_fma_f32 v[122:123], v[130:131], v[122:123], v[144:145] op_sel_hi:[0,1,1]
	v_pk_fma_f32 v[124:125], v[130:131], v[124:125], v[146:147] op_sel_hi:[0,1,1]
	v_pk_fma_f32 v[126:127], v[130:131], v[126:127], v[140:141] op_sel_hi:[0,1,1]
	v_pk_mul_f32 v[140:141], v[122:123], v[122:123]
	v_and_b32_e32 v161, 0xffff0000, v143
	v_lshlrev_b32_e32 v160, 16, v143
	v_pk_mul_f32 v[142:143], v[124:125], v[124:125]
	v_add_f32_e32 v0, v140, v141
	v_add_f32_e32 v0, v142, v0
	v_pk_mul_f32 v[144:145], v[126:127], v[126:127]
	v_add_f32_e32 v0, v143, v0
	v_pk_fma_f32 v[128:129], v[130:131], v[128:129], v[160:161] op_sel_hi:[0,1,1]
	v_add_f32_e32 v0, v144, v0
	v_pk_mul_f32 v[146:147], v[128:129], v[128:129]
	v_add_f32_e32 v0, v145, v0
	v_add_f32_e32 v0, v146, v0
	v_cvt_pk_bf16_f32 v122, v122, v123
	v_cvt_pk_bf16_f32 v123, v124, v125
	v_cvt_pk_bf16_f32 v124, v126, v127
	v_cvt_pk_bf16_f32 v125, v128, v129
	v_add_f32_e32 v140, v147, v0
	global_store_dwordx4 v[138:139], v[122:125], off

; __device__ __forceinline__ float bfs(short h) { return __uint_as_float(((unsigned)(u16)h) << 16); }
; template <int lda, int K>
; __device__ __forceinline__ void phase_resid(PP p, const int g_wid, const u16* Abase, const u16* Btbase, const float alpha_in) {
;     ...
;     const unsigned tok0 = wc * 32 + fr;
; #pragma unroll
;     for (int bj = 0; bj < 2; ++bj)
; #pragma unroll
;       for (int n = 0; n < 2; ++n) {
;         const int row = pm * 256 + tok0 + bj * 128 + n * 16;
;         const bool ok = row < NTOK;
;         float sq = 0.f;
;         u16* hbr = p->hb + (long)row * 1024 + pn * 256 + wr * 64 + SWAP_FOFF(fq);
; #pragma unroll
;         for (int ai = 0; ai < 2; ++ai)
; #pragma unroll
;           for (int mp = 0; mp < 4; mp += 2) {
;             float v[8];
; #pragma unroll
;             for (int j = 0; j < 4; ++j) {
;               auto r = __builtin_amdgcn_permlane16_swap(__float_as_uint(acc[ai][bj][mp][n][j]), __float_as_uint(acc[ai][bj][mp + 1][n][j]), false, false);
;               v[j] = __uint_as_float(r[0]); v[4 + j] = __uint_as_float(r[1]);
;             }
;             if (ok) {
;               const bf16x8 ho = *reinterpret_cast<const bf16x8*>(hbr + ai * 128 + mp * 16);
; #pragma unroll
;               for (int j = 0; j < 8; ++j) { v[j] = bfs(ho[j]) + alpha * v[j]; sq += v[j] * v[j]; }
;               *reinterpret_cast<uint4*>(hbr + ai * 128 + mp * 16) = make_uint4(pack2(v[0], v[1]), pack2(v[2], v[3]), pack2(v[4], v[5]), pack2(v[6], v[7]));
.LBB0_491:
	s_or_b64 exec, exec, s[10:11]
	s_mov_b32 s3, -1
	s_sext_i32_i16 s14, s8
	v_mbcnt_lo_u32_b32 v0, s3, 0
	v_mbcnt_hi_u32_b32 v0, s3, v0
	v_readlane_b32 s3, v254, 63
	v_readlane_b32 s8, v254, 0
	v_readlane_b32 s9, v254, 1
	v_or_b32_e32 v0, s3, v0
	s_load_dwordx2 s[10:11], s[8:9], 0xc8
	s_nop 0
	s_load_dwordx2 s[8:9], s[8:9], 0xe0
	v_lshrrev_b32_e32 v133, 1, v0
	v_and_b32_e32 v132, 15, v0
	v_and_b32_e32 v133, 0x60, v133
	s_lshl_b32 s2, s2, 8
	v_or3_b32 v132, v132, v133, s2
	s_lshl_b32 s2, s14, 8
	v_bfe_u32 v131, v0, 4, 2
	s_ashr_i32 s3, s2, 31
	v_ashrrev_i32_e32 v136, 8, v0
	s_lshl_b64 s[2:3], s[2:3], 1
	v_and_b32_e32 v0, 16, v0
	v_lshlrev_b32_e32 v133, 2, v131
	s_waitcnt lgkmcnt(0)
	s_add_u32 s2, s10, s2
	v_lshlrev_b32_e32 v134, 6, v136
	v_add_u32_e32 v137, 12, v133
	v_cmp_eq_u32_e32 vcc, 0, v0
	s_addc_u32 s3, s11, s3
	v_ashrrev_i32_e32 v135, 31, v134
	v_cndmask_b32_e32 v0, v137, v133, vcc
	v_lshl_add_u64 v[134:135], v[134:135], 1, s[2:3]
	v_lshlrev_b32_e32 v0, 1, v0
	v_ashrrev_i32_e32 v133, 31, v132
	v_lshl_add_u64 v[134:135], v[134:135], 0, v[0:1]
	v_lshlrev_b64 v[138:139], 11, v[132:133]
	v_mov_b32_e32 v130, 1.0
	v_cmp_gt_i32_e64 s[2:3], s47, v132
	v_lshl_add_u64 v[138:139], v[134:135], 0, v[138:139]
	v_and_b32_e32 v248, 15, v132
	v_lshl_or_b32 v245, v131, 4, v248
	v_lshrrev_b32_e32 v249, 5, v132
	v_and_b32_e32 v249, 3, v249
	v_lshl_or_b32 v249, v136, 2, v249
	v_lshlrev_b32_e32 v249, 14, v249
	v_and_b32_e32 v242, 1, v131
	v_lshrrev_b32_e32 v243, 1, v131
	v_lshl_or_b32 v243, v242, 1, v243
	v_and_b32_e32 v242, 7, v248
	v_xor_b32_e32 v242, v243, v242
	v_lshlrev_b32_e32 v242, 4, v242
	v_lshl_add_u32 v244, v248, 7, v249
	v_add_u32_e32 v242, v244, v242
	v_lshlrev_b32_e32 v243, 4, v243
	v_lshl_add_u32 v248, v248, 11, v243
	v_xor_b32_e32 v243, 64, v242
	v_lshrrev_b32_e32 v244, 3, v245
	v_and_b32_e32 v245, 7, v245
	v_lshlrev_b32_e32 v246, 4, v245
	v_lshl_add_u32 v246, v244, 11, v246
	v_sub_u32_e32 v246, v246, v248
	v_ashrrev_i32_e32 v247, 31, v246
	v_lshl_add_u64 v[246:247], v[138:139], 0, v[246:247]
	v_xor_b32_e32 v245, v245, v244
	v_lshlrev_b32_e32 v245, 4, v245
	v_lshl_add_u32 v244, v244, 7, v249
	v_add_u32_e32 v244, v244, v245
	global_load_dwordx4 v[178:181], v[246:247], off
	global_load_dwordx4 v[186:189], v[246:247], off offset:256
	v_add_co_u32_e32 v246, vcc, 0x4000, v246
	s_nop 1
	v_addc_co_u32_e32 v247, vcc, 0, v247, vcc
	global_load_dwordx4 v[182:185], v[246:247], off
	global_load_dwordx4 v[190:193], v[246:247], off offset:256
	v_add_co_u32_e32 v246, vcc, 0x4000, v246
	s_nop 1
	v_addc_co_u32_e32 v247, vcc, 0, v247, vcc
	global_load_dwordx4 v[194:197], v[246:247], off
	global_load_dwordx4 v[202:205], v[246:247], off offset:256
	v_add_co_u32_e32 v246, vcc, 0x4000, v246
	s_nop 1
	v_addc_co_u32_e32 v247, vcc, 0, v247, vcc
	global_load_dwordx4 v[198:201], v[246:247], off
	global_load_dwordx4 v[206:209], v[246:247], off offset:256
	v_add_co_u32_e32 v246, vcc, 0x34000, v246
	s_nop 1
	v_addc_co_u32_e32 v247, vcc, 0, v247, vcc
	global_load_dwordx4 v[210:213], v[246:247], off
	global_load_dwordx4 v[218:221], v[246:247], off offset:256
	v_add_co_u32_e32 v246, vcc, 0x4000, v246
	s_nop 1
	v_addc_co_u32_e32 v247, vcc, 0, v247, vcc
	global_load_dwordx4 v[214:217], v[246:247], off
	global_load_dwordx4 v[222:225], v[246:247], off offset:256
	v_add_co_u32_e32 v246, vcc, 0x4000, v246
	s_nop 1
	v_addc_co_u32_e32 v247, vcc, 0, v247, vcc
	global_load_dwordx4 v[226:229], v[246:247], off
	global_load_dwordx4 v[234:237], v[246:247], off offset:256
	v_add_co_u32_e32 v246, vcc, 0x4000, v246
	s_nop 1
	v_addc_co_u32_e32 v247, vcc, 0, v247, vcc
	global_load_dwordx4 v[230:233], v[246:247], off
	global_load_dwordx4 v[238:241], v[246:247], off offset:256
	s_waitcnt vmcnt(0)
	ds_write_b128 v244, v[178:181]
	ds_write_b128 v244, v[182:185] offset:1024
	ds_write_b128 v244, v[186:189] offset:2048
	ds_write_b128 v244, v[190:193] offset:3072
	ds_write_b128 v244, v[194:197] offset:4096
	ds_write_b128 v244, v[198:201] offset:5120
	ds_write_b128 v244, v[202:205] offset:6144
	ds_write_b128 v244, v[206:209] offset:7168
	ds_write_b128 v244, v[210:213] offset:8192
	ds_write_b128 v244, v[214:217] offset:9216
	ds_write_b128 v244, v[218:221] offset:10240
	ds_write_b128 v244, v[222:225] offset:11264
	ds_write_b128 v244, v[226:229] offset:12288
	ds_write_b128 v244, v[230:233] offset:13312
	ds_write_b128 v244, v[234:237] offset:14336
	ds_write_b128 v244, v[238:241] offset:15360
	ds_read_b128 v[178:181], v242
	ds_read_b128 v[182:185], v243
	ds_read_b128 v[186:189], v242 offset:2048
	ds_read_b128 v[190:193], v243 offset:2048
	ds_read_b128 v[194:197], v242 offset:4096
	ds_read_b128 v[198:201], v243 offset:4096
	ds_read_b128 v[202:205], v242 offset:6144
	ds_read_b128 v[206:209], v243 offset:6144
	ds_read_b128 v[210:213], v242 offset:8192
	ds_read_b128 v[214:217], v243 offset:8192
	ds_read_b128 v[218:221], v242 offset:10240
	ds_read_b128 v[222:225], v243 offset:10240
	ds_read_b128 v[226:229], v242 offset:12288
	ds_read_b128 v[230:233], v243 offset:12288
	ds_read_b128 v[234:237], v242 offset:14336
	ds_read_b128 v[238:241], v243 offset:14336
	s_waitcnt lgkmcnt(0)
	s_barrier
	v_permlane16_swap_b32_e32 v122, v126
	v_permlane16_swap_b32_e32 v123, v127
	v_permlane16_swap_b32_e32 v124, v128
	v_permlane16_swap_b32_e32 v125, v129
	v_mov_b32_e32 v140, 0
	s_and_saveexec_b64 s[10:11], s[2:3]
	s_cbranch_execz .LBB0_493
	s_waitcnt vmcnt(15)
	v_mov_b64_e32 v[140:141], v[178:179]
	v_mov_b64_e32 v[142:143], v[180:181]
	v_and_b32_e32 v145, 0xffff0000, v140
	v_lshlrev_b32_e32 v144, 16, v140
	v_and_b32_e32 v147, 0xffff0000, v141
	v_lshlrev_b32_e32 v146, 16, v141
	v_and_b32_e32 v141, 0xffff0000, v142
	v_lshlrev_b32_e32 v140, 16, v142
	v_pk_fma_f32 v[122:123], v[130:131], v[122:123], v[144:145] op_sel_hi:[0,1,1]
	v_pk_fma_f32 v[124:125], v[130:131], v[124:125], v[146:147] op_sel_hi:[0,1,1]
	v_pk_fma_f32 v[126:127], v[130:131], v[126:127], v[140:141] op_sel_hi:[0,1,1]
	v_pk_mul_f32 v[140:141], v[122:123], v[122:123]
	v_and_b32_e32 v161, 0xffff0000, v143
	v_lshlrev_b32_e32 v160, 16, v143
	v_pk_mul_f32 v[142:143], v[124:125], v[124:125]
	v_add_f32_e32 v0, v140, v141
	v_add_f32_e32 v0, v142, v0
	v_pk_mul_f32 v[144:145], v[126:127], v[126:127]
	v_add_f32_e32 v0, v143, v0
	v_pk_fma_f32 v[128:129], v[130:131], v[128:129], v[160:161] op_sel_hi:[0,1,1]
	v_add_f32_e32 v0, v144, v0
	v_pk_mul_f32 v[146:147], v[128:129], v[128:129]
	v_add_f32_e32 v0, v145, v0
	v_add_f32_e32 v0, v146, v0
	v_cvt_pk_bf16_f32 v122, v122, v123
	v_cvt_pk_bf16_f32 v123, v124, v125
	v_cvt_pk_bf16_f32 v124, v126, v127
	v_cvt_pk_bf16_f32 v125, v128, v129
	v_add_f32_e32 v140, v147, v0
	global_store_dwordx4 v[138:139], v[122:125], off
